# e41 + e26b: ctx rows (ninth rmsnorm row) moved from the S5-table workgroups vcu<64 to workgroups vcu>=192
# speedup vs baseline: 1.0198x; 1.0043x over previous
; __device__ __forceinline__ f32x4 ld_nt(const float* p) { return __builtin_nontemporal_load((const f32x4*)p); }
; __device__ __forceinline__ void norm_rows(int gw, int lane, const float* x, const float* ctx, const float* ng, const float* mod, f16* h) {
;     f32x4 gs[8], sh[8];
;     auto load_mod = [&](int mr) { const float* shp = mod + mr * 3 * D;
; #pragma unroll
;         for (int j = 0; j < 8; ++j) { const int cidx = 256 * j + 4 * lane; const f32x4 g4 = *(const f32x4*)(ng + cidx), s4 = *(const f32x4*)(shp + D + cidx); gs[j] = g4 * (1.f + s4); sh[j] = *(const f32x4*)(shp + cidx); } };
;     auto finish_row = [&](const f32x4 (&v)[8], f16* dst) { float ss = 0.f;
; #pragma unroll
;         for (int j = 0; j < 8; ++j) ss += (v[j][0] * v[j][0] + v[j][1] * v[j][1]) + (v[j][2] * v[j][2] + v[j][3] * v[j][3]);
;         const float rstd = rsqrtf(wave_sum(ss) * (1.f / D) + EPS);
; #pragma unroll
;         for (int j = 0; j < 8; ++j) { const f32x4 o = v[j] * rstd * gs[j] + sh[j]; u32x2 w; w.x = pk_f16(o[0], o[1]); w.y = pk_f16(o[2], o[3]); *(u32x2*)(dst + 256 * j + 4 * lane) = w; } };
;     constexpr int RPW = 8;
;     const int r0 = gw * RPW;
;     if (r0 < M_LAT) { load_mod(r0 / SEQ);
; #pragma unroll 1
;         for (int rb = r0; rb < r0 + RPW; rb += 4) { f32x4 v[4][8];
; #pragma unroll
;             for (int rr = 0; rr < 4; ++rr)
; #pragma unroll
;                 for (int j = 0; j < 8; ++j) v[rr][j] = ld_nt(x + (size_t)(rb + rr) * D + 256 * j + 4 * lane);
;             __builtin_amdgcn_sched_barrier(0);
; #pragma unroll
;             for (int rr = 0; rr < 4; ++rr) finish_row(v[rr], h + (size_t)(rb + rr) * D); } }
;     if (gw < M_CTX) { load_mod(2); f32x4 v[8];
; #pragma unroll
;         for (int j = 0; j < 8; ++j) v[j] = ld_nt(ctx + (size_t)gw * D + 256 * j + 4 * lane);
;         finish_row(v, h + (size_t)(M_LAT + gw) * D); }
.LBB0_182:
	s_sub_i32 s6, s6, 0x600
	s_cmp_lt_i32 s6, 0
	s_cbranch_scc1 .Lctx_back
	s_add_u32 s2, s50, 0x10c000
	s_addc_u32 s3, s51, 0
	s_add_u32 s10, s50, 0x10e000
	s_addc_u32 s11, s51, 0
	s_ashr_i32 s7, s6, 31
	v_readlane_b32 s56, v254, 2
	v_or_b32_e32 v1, 0x400, v162
	s_lshl_b64 s[8:9], s[6:7], 13
	v_readlane_b32 s60, v254, 6
	global_load_dwordx4 v[50:53], v162, s[10:11]
	global_load_dwordx4 v[54:57], v1, s[10:11]
	v_or_b32_e32 v34, 0x800, v162
	v_readlane_b32 s61, v254, 7
	s_add_u32 s8, s60, s8
	global_load_dwordx4 v[58:61], v34, s[10:11]
	v_or_b32_e32 v35, 0xc00, v162
	v_or_b32_e32 v22, 0x1000, v162
	v_or_b32_e32 v133, 0x1400, v162
	s_addc_u32 s9, s61, s9
	global_load_dwordx4 v[62:65], v35, s[10:11]
	global_load_dwordx4 v[66:69], v22, s[10:11]
	global_load_dwordx4 v[70:73], v133, s[10:11]
	global_load_dwordx4 v[42:45], v162, s[8:9] nt
	global_load_dwordx4 v[30:33], v162, s[8:9] offset:1024 nt
	global_load_dwordx4 v[26:29], v162, s[8:9] offset:2048 nt
	global_load_dwordx4 v[18:21], v162, s[8:9] offset:3072 nt
	v_mov_b32_e32 v163, 0
	s_movk_i32 s12, 0x1000
	v_lshl_add_u64 v[2:3], s[8:9], 0, v[162:163]
	v_add_co_u32_e32 v6, vcc, s12, v2
	v_readlane_b32 s68, v254, 14
	s_nop 0
	v_addc_co_u32_e32 v7, vcc, 0, v3, vcc
	v_readlane_b32 s69, v254, 15
	global_load_dwordx4 v[14:17], v[6:7], off nt
	global_load_dwordx4 v[10:13], v[6:7], off offset:1024 nt
	global_load_dwordx4 v[2:5], v[6:7], off offset:3072 nt
	s_nop 0
	global_load_dwordx4 v[6:9], v[6:7], off offset:2048 nt
	s_nop 0
	global_load_dwordx4 v[74:77], v162, s[68:69]
	global_load_dwordx4 v[78:81], v162, s[68:69] offset:1024
	global_load_dwordx4 v[82:85], v162, s[68:69] offset:2048
	global_load_dwordx4 v[86:89], v162, s[68:69] offset:3072
	v_or_b32_e32 v136, 0x1800, v162
	v_or_b32_e32 v137, 0x1c00, v162
	global_load_dwordx4 v[90:93], v133, s[68:69]
	global_load_dwordx4 v[94:97], v136, s[68:69]
	global_load_dwordx4 v[98:101], v137, s[68:69]
	global_load_dwordx4 v[102:105], v22, s[68:69]
	s_nop 0
	global_load_dwordx4 v[22:25], v22, s[2:3]
	s_nop 0
	global_load_dwordx4 v[106:109], v162, s[2:3]
	global_load_dwordx4 v[46:49], v1, s[2:3]
	global_load_dwordx4 v[38:41], v34, s[2:3]
	s_nop 0
	global_load_dwordx4 v[34:37], v35, s[2:3]
	s_nop 0
	global_load_dwordx4 v[110:113], v136, s[10:11]
	global_load_dwordx4 v[114:117], v137, s[10:11]
	v_lshlrev_b32_e32 v162, 3, v212
	v_readlane_b32 s57, v254, 3
	v_readlane_b32 s58, v254, 4
	v_readlane_b32 s59, v254, 5
	v_readlane_b32 s62, v254, 8
	v_readlane_b32 s63, v254, 9
	v_readlane_b32 s64, v254, 10
	v_readlane_b32 s65, v254, 11
	v_readlane_b32 s66, v254, 12
	v_readlane_b32 s67, v254, 13
	v_readlane_b32 s70, v254, 16
	v_readlane_b32 s71, v254, 17
	s_waitcnt vmcnt(0)
	v_pk_add_f32 v[118:119], v[52:53], 1.0 op_sel_hi:[1,0]
	v_pk_add_f32 v[122:123], v[56:57], 1.0 op_sel_hi:[1,0]
	v_pk_add_f32 v[120:121], v[50:51], 1.0 op_sel_hi:[1,0]
	v_pk_add_f32 v[124:125], v[54:55], 1.0 op_sel_hi:[1,0]
	v_pk_add_f32 v[126:127], v[60:61], 1.0 op_sel_hi:[1,0]
	v_pk_add_f32 v[128:129], v[58:59], 1.0 op_sel_hi:[1,0]
	v_mov_b32_e32 v52, v43
	v_mov_b32_e32 v53, v31
	v_mov_b32_e32 v56, v45
	v_mov_b32_e32 v57, v33
	v_mov_b32_e32 v50, v42
	v_mov_b32_e32 v51, v30
	v_mov_b32_e32 v54, v44
	v_mov_b32_e32 v55, v32
	v_pk_mul_f32 v[58:59], v[28:29], v[28:29]
	v_pk_mul_f32 v[60:61], v[26:27], v[26:27]
	v_pk_mul_f32 v[52:53], v[52:53], v[52:53]
	v_pk_mul_f32 v[56:57], v[56:57], v[56:57]
	v_pk_mov_b32 v[134:135], v[60:61], v[58:59] op_sel:[1,0]
	v_mov_b32_e32 v61, v59
	v_pk_fma_f32 v[50:51], v[50:51], v[50:51], v[52:53]
	v_pk_fma_f32 v[52:53], v[54:55], v[54:55], v[56:57]
	v_mul_f32_e32 v130, v19, v19
	v_mul_f32_e32 v132, v21, v21
	v_pk_add_f32 v[54:55], v[134:135], v[60:61]
	v_pk_add_f32 v[50:51], v[50:51], v[52:53]
	v_pk_fma_f32 v[58:59], v[18:19], v[18:19], v[130:131] op_sel_hi:[1,1,0]
	v_pk_fma_f32 v[130:131], v[20:21], v[20:21], v[132:133] op_sel_hi:[1,1,0]
	v_mul_f32_e32 v1, v14, v14
	v_mul_f32_e32 v56, v15, v15
	v_pk_add_f32 v[52:53], v[54:55], v[54:55] op_sel:[0,1] op_sel_hi:[1,0]
	v_pk_add_f32 v[50:51], v[50:51], v[50:51] op_sel:[0,1] op_sel_hi:[1,0]
	v_mul_f32_e32 v59, v16, v16
	v_mul_f32_e32 v131, v17, v17
	v_mov_b32_e32 v53, v56
	v_mov_b32_e32 v51, v1
	v_pk_add_f32 v[50:51], v[50:51], v[52:53]
	v_pk_add_f32 v[52:53], v[58:59], v[130:131]
	v_pk_mul_f32 v[54:55], v[10:11], v[10:11]
	v_pk_add_f32 v[50:51], v[50:51], v[52:53]
	v_pk_mul_f32 v[52:53], v[12:13], v[12:13]
	v_mul_f32_e32 v1, v2, v2
	v_pk_mov_b32 v[56:57], v[54:55], v[52:53] op_sel:[1,0]
	v_mov_b32_e32 v55, v53
	v_pk_add_f32 v[52:53], v[56:57], v[54:55]
	v_mul_f32_e32 v54, v3, v3
	v_pk_add_f32 v[50:51], v[50:51], v[50:51] op_sel:[0,1] op_sel_hi:[1,0]
	v_pk_add_f32 v[52:53], v[52:53], v[52:53] op_sel:[0,1] op_sel_hi:[1,0]
	v_mov_b32_e32 v51, v1
	v_mov_b32_e32 v53, v54
	v_pk_add_f32 v[50:51], v[50:51], v[52:53]
	v_mul_f32_e32 v52, v7, v7
	v_mul_f32_e32 v55, v4, v4
	v_pk_fma_f32 v[52:53], v[6:7], v[6:7], v[52:53] op_sel_hi:[1,1,0]
	v_mul_f32_e32 v54, v9, v9
	v_mul_f32_e32 v56, v5, v5
	v_mov_b32_e32 v53, v55
	v_pk_fma_f32 v[54:55], v[8:9], v[8:9], v[54:55] op_sel_hi:[1,1,0]
	global_load_dwordx4 v[58:61], v137, s[2:3]
	v_mov_b32_e32 v55, v56
	v_pk_add_f32 v[52:53], v[52:53], v[54:55]
	v_pk_mul_f32 v[76:77], v[76:77], v[118:119]
	v_pk_add_f32 v[50:51], v[50:51], v[52:53]
	v_pk_add_f32 v[62:63], v[62:63], 1.0 op_sel_hi:[1,0]
	v_add_f32_e32 v1, v50, v51
	v_mbcnt_lo_u32_b32 v50, -1, 0
	v_mbcnt_hi_u32_b32 v130, -1, v50
	v_and_b32_e32 v50, 64, v130
	v_add_u32_e32 v131, 64, v50
	v_xor_b32_e32 v50, 1, v130
	v_cmp_lt_i32_e32 vcc, v50, v131
	v_xor_b32_e32 v118, 8, v130
	v_pk_mul_f32 v[62:63], v[86:87], v[62:63]
	v_cndmask_b32_e32 v50, v130, v50, vcc
	v_lshlrev_b32_e32 v50, 2, v50
	ds_bpermute_b32 v54, v50, v1
	global_load_dwordx4 v[50:53], v133, s[2:3]
	v_xor_b32_e32 v86, 16, v130
	v_pk_add_f32 v[66:67], v[66:67], 1.0 op_sel_hi:[1,0]
	v_pk_add_f32 v[64:65], v[64:65], 1.0 op_sel_hi:[1,0]
	s_waitcnt lgkmcnt(0)
; __device__ __forceinline__ void norm_rows(int gw, int lane, const float* x, const float* ctx, const float* ng, const float* mod, f16* h) {
;     ...
;     auto finish_row = [&](const f32x4 (&v)[8], f16* dst) { float ss = 0.f;
; #pragma unroll
;         for (int j = 0; j < 8; ++j) ss += (v[j][0] * v[j][0] + v[j][1] * v[j][1]) + (v[j][2] * v[j][2] + v[j][3] * v[j][3]);
;         const float rstd = rsqrtf(wave_sum(ss) * (1.f / D) + EPS);
; #pragma unroll
;         for (int j = 0; j < 8; ++j) { const f32x4 o = v[j] * rstd * gs[j] + sh[j]; u32x2 w; w.x = pk_f16(o[0], o[1]); w.y = pk_f16(o[2], o[3]); *(u32x2*)(dst + 256 * j + 4 * lane) = w; } };
	v_add_f32_e32 v1, v1, v54
	v_xor_b32_e32 v54, 2, v130
	v_cmp_lt_i32_e32 vcc, v54, v131
	v_pk_mul_f32 v[66:67], v[102:103], v[66:67]
	v_pk_add_f32 v[110:111], v[110:111], 1.0 op_sel_hi:[1,0]
	v_cndmask_b32_e32 v54, v130, v54, vcc
	v_lshlrev_b32_e32 v54, 2, v54
	ds_bpermute_b32 v132, v54, v1
	global_load_dwordx4 v[54:57], v136, s[2:3]
	v_pk_mul_f32 v[64:65], v[88:89], v[64:65]
	v_pk_mul_f32 v[88:89], v[94:95], v[110:111]
	v_mov_b32_e32 v94, 0x358637bd
	s_waitcnt lgkmcnt(0)
	v_add_f32_e32 v1, v1, v132
	v_xor_b32_e32 v132, 4, v130
	v_cmp_lt_i32_e32 vcc, v132, v131
	s_mov_b32 s2, 0x800000
	v_pk_mul_f32 v[74:75], v[74:75], v[120:121]
	v_cndmask_b32_e32 v132, v130, v132, vcc
	v_lshlrev_b32_e32 v132, 2, v132
	ds_bpermute_b32 v132, v132, v1
	v_cmp_lt_i32_e32 vcc, v118, v131
	v_pk_add_f32 v[68:69], v[68:69], 1.0 op_sel_hi:[1,0]
	v_pk_add_f32 v[72:73], v[72:73], 1.0 op_sel_hi:[1,0]
	v_cndmask_b32_e32 v118, v130, v118, vcc
	s_waitcnt lgkmcnt(0)
	v_add_f32_e32 v1, v1, v132
	v_lshlrev_b32_e32 v118, 2, v118
	ds_bpermute_b32 v118, v118, v1
	v_cmp_lt_i32_e32 vcc, v86, v131
	v_pk_add_f32 v[70:71], v[70:71], 1.0 op_sel_hi:[1,0]
	v_pk_add_f32 v[112:113], v[112:113], 1.0 op_sel_hi:[1,0]
	v_cndmask_b32_e32 v86, v130, v86, vcc
	s_waitcnt lgkmcnt(0)
	v_add_f32_e32 v1, v1, v118
	v_lshlrev_b32_e32 v86, 2, v86
	ds_bpermute_b32 v86, v86, v1
	v_pk_add_f32 v[116:117], v[116:117], 1.0 op_sel_hi:[1,0]
	v_pk_add_f32 v[114:115], v[114:115], 1.0 op_sel_hi:[1,0]
	v_pk_mul_f32 v[80:81], v[80:81], v[122:123]
	v_pk_mul_f32 v[78:79], v[78:79], v[124:125]
	s_waitcnt lgkmcnt(0)
	v_add_f32_e32 v1, v1, v86
	v_xor_b32_e32 v86, 32, v130
	v_cmp_lt_i32_e32 vcc, v86, v131
	v_pk_mul_f32 v[84:85], v[84:85], v[126:127]
	v_pk_mul_f32 v[82:83], v[82:83], v[128:129]
	v_cndmask_b32_e32 v86, v130, v86, vcc
	v_lshlrev_b32_e32 v86, 2, v86
	ds_bpermute_b32 v102, v86, v1
	v_pk_mul_f32 v[68:69], v[104:105], v[68:69]
	v_pk_mul_f32 v[72:73], v[92:93], v[72:73]
	v_pk_mul_f32 v[70:71], v[90:91], v[70:71]
	v_pk_mul_f32 v[86:87], v[96:97], v[112:113]
	s_waitcnt lgkmcnt(0)
	v_add_f32_e32 v1, v1, v102
	v_fmac_f32_e32 v94, 0x3a000000, v1
	v_mul_f32_e32 v1, 0x4b800000, v94
	v_cmp_gt_f32_e32 vcc, s2, v94
	s_lshl_b64 s[2:3], s[6:7], 12
	s_add_u32 s2, s50, s2
	v_cndmask_b32_e32 v1, v94, v1, vcc
	v_rsq_f32_e32 v1, v1
	s_addc_u32 s3, s51, s3
	v_pk_mul_f32 v[90:91], v[100:101], v[116:117]
	v_pk_mul_f32 v[92:93], v[98:99], v[114:115]
	v_mul_f32_e32 v94, 0x45800000, v1
	v_cndmask_b32_e32 v94, v1, v94, vcc
	v_pk_mul_f32 v[42:43], v[42:43], v[94:95] op_sel_hi:[1,0]
	v_pk_mul_f32 v[44:45], v[44:45], v[94:95] op_sel_hi:[1,0]
	v_pk_fma_f32 v[42:43], v[74:75], v[42:43], v[106:107]
	v_pk_fma_f32 v[44:45], v[76:77], v[44:45], v[108:109]
	v_cvt_pk_bf16_f32 v42, v42, v43
	v_cvt_pk_bf16_f32 v43, v44, v45
	v_lshl_add_u64 v[44:45], s[2:3], 0, v[162:163]
	s_mov_b64 s[2:3], 0xa100000
	v_lshl_add_u64 v[74:75], v[44:45], 0, s[2:3]
	s_mov_b32 s2, 0xa100000
	v_pk_mul_f32 v[30:31], v[30:31], v[94:95] op_sel_hi:[1,0]
	v_pk_mul_f32 v[32:33], v[32:33], v[94:95] op_sel_hi:[1,0]
	v_pk_mul_f32 v[26:27], v[26:27], v[94:95] op_sel_hi:[1,0]
	v_pk_mul_f32 v[28:29], v[28:29], v[94:95] op_sel_hi:[1,0]
	v_pk_mul_f32 v[18:19], v[18:19], v[94:95] op_sel_hi:[1,0]
	v_pk_mul_f32 v[20:21], v[20:21], v[94:95] op_sel_hi:[1,0]
	v_pk_mul_f32 v[14:15], v[14:15], v[94:95] op_sel_hi:[1,0]
	v_pk_mul_f32 v[16:17], v[16:17], v[94:95] op_sel_hi:[1,0]
	v_pk_mul_f32 v[10:11], v[10:11], v[94:95] op_sel_hi:[1,0]
	v_pk_mul_f32 v[12:13], v[12:13], v[94:95] op_sel_hi:[1,0]
	v_pk_mul_f32 v[6:7], v[6:7], v[94:95] op_sel_hi:[1,0]
	v_pk_mul_f32 v[8:9], v[8:9], v[94:95] op_sel_hi:[1,0]
	v_pk_mul_f32 v[2:3], v[2:3], v[94:95] op_sel_hi:[1,0]
	v_pk_mul_f32 v[4:5], v[4:5], v[94:95] op_sel_hi:[1,0]
	v_add_co_u32_e32 v44, vcc, s2, v44
	v_pk_fma_f32 v[32:33], v[80:81], v[32:33], v[48:49]
	v_pk_fma_f32 v[30:31], v[78:79], v[30:31], v[46:47]
	v_pk_fma_f32 v[28:29], v[84:85], v[28:29], v[40:41]
	v_pk_fma_f32 v[26:27], v[82:83], v[26:27], v[38:39]
	v_pk_fma_f32 v[20:21], v[64:65], v[20:21], v[36:37]
	v_pk_fma_f32 v[18:19], v[62:63], v[18:19], v[34:35]
	v_pk_fma_f32 v[16:17], v[68:69], v[16:17], v[24:25]
	v_pk_fma_f32 v[14:15], v[66:67], v[14:15], v[22:23]
	s_waitcnt vmcnt(1)
	v_pk_fma_f32 v[12:13], v[72:73], v[12:13], v[52:53]
	v_pk_fma_f32 v[10:11], v[70:71], v[10:11], v[50:51]
	s_waitcnt vmcnt(0)
	v_pk_fma_f32 v[8:9], v[86:87], v[8:9], v[56:57]
	v_pk_fma_f32 v[6:7], v[88:89], v[6:7], v[54:55]
	v_pk_fma_f32 v[4:5], v[90:91], v[4:5], v[60:61]
	v_pk_fma_f32 v[2:3], v[92:93], v[2:3], v[58:59]
	v_addc_co_u32_e32 v45, vcc, 0, v45, vcc
	v_cvt_pk_bf16_f32 v30, v30, v31
	v_cvt_pk_bf16_f32 v31, v32, v33
	v_cvt_pk_bf16_f32 v26, v26, v27
	v_cvt_pk_bf16_f32 v27, v28, v29
	v_cvt_pk_bf16_f32 v18, v18, v19
	v_cvt_pk_bf16_f32 v19, v20, v21
	v_cvt_pk_bf16_f32 v14, v14, v15
	v_cvt_pk_bf16_f32 v15, v16, v17
	v_cvt_pk_bf16_f32 v10, v10, v11
	v_cvt_pk_bf16_f32 v11, v12, v13
	v_cvt_pk_bf16_f32 v6, v6, v7
	v_cvt_pk_bf16_f32 v7, v8, v9
	v_cvt_pk_bf16_f32 v2, v2, v3
	v_cvt_pk_bf16_f32 v3, v4, v5
	global_store_dwordx2 v[44:45], v[42:43], off
	global_store_dwordx2 v[74:75], v[30:31], off offset:512
	global_store_dwordx2 v[74:75], v[26:27], off offset:1024
	global_store_dwordx2 v[74:75], v[18:19], off offset:1536
	global_store_dwordx2 v[74:75], v[14:15], off offset:2048
	global_store_dwordx2 v[74:75], v[10:11], off offset:2560
	global_store_dwordx2 v[74:75], v[6:7], off offset:3072
	global_store_dwordx2 v[74:75], v[2:3], off offset:3584
.Lctx_back:
	s_add_i32 s6, s6, 0x600
